# A/B: reversed priority polarity in GEMM K-loops: load segments at s_setprio 2, MFMA segments at 0
# baseline (speedup 1.0000x reference)
.LBB0_169:
	s_setprio 2
	s_add_u32 s42, s40, 0xfff80080
	s_addc_u32 s43, s41, -1
	s_add_i32 s52, 0, 0x10000
	s_cmp_eq_u32 s51, 28
	s_cselect_b32 s45, s13, s43
	s_cselect_b32 s44, s47, s42
	s_cselect_b32 s43, s11, s50
	s_cselect_b32 s42, s48, s49
	s_add_i32 s54, 0, 0x14000
	ds_read_b128 v[130:133], v236
	ds_read_b128 v[134:137], v236 offset:1024
	ds_read_b128 v[138:141], v236 offset:2048
	ds_read_b128 v[142:145], v236 offset:3072
	ds_read_b128 v[170:173], v237
	ds_read_b128 v[184:187], v237 offset:1024
	ds_read_b128 v[188:191], v237 offset:2048
	ds_read_b128 v[192:195], v237 offset:3072
	s_add_i32 m0, s14, 0xc000
	ds_read_b128 v[196:199], v183
	ds_read_b128 v[200:203], v183 offset:1024
	ds_read_b128 v[210:213], v183 offset:2048
	ds_read_b128 v[214:217], v183 offset:3072
	ds_read_b128 v[218:221], v183 offset:4096
	ds_read_b128 v[222:225], v183 offset:5120
	ds_read_b128 v[226:229], v183 offset:6144
	ds_read_b128 v[230:233], v183 offset:7168
	global_load_lds_dwordx4 v166, s[40:41]
	s_add_i32 m0, s14, 0xe000
	s_nop 0
	global_load_lds_dwordx4 v168, s[40:41]
	s_setprio 0
	s_waitcnt vmcnt(8) lgkmcnt(0)
	s_barrier
	v_mfma_f32_16x16x32_bf16 v[126:129], v[130:133], v[196:199], v[126:129]
	v_mfma_f32_16x16x32_bf16 v[122:125], v[138:141], v[196:199], v[122:125]
	v_mfma_f32_16x16x32_bf16 v[118:121], v[130:133], v[210:213], v[118:121]
	v_mfma_f32_16x16x32_bf16 v[110:113], v[138:141], v[210:213], v[110:113]
	v_mfma_f32_16x16x32_bf16 v[102:105], v[130:133], v[218:221], v[102:105]
	v_mfma_f32_16x16x32_bf16 v[94:97], v[138:141], v[218:221], v[94:97]
	v_mfma_f32_16x16x32_bf16 v[86:89], v[130:133], v[226:229], v[86:89]
	v_mfma_f32_16x16x32_bf16 v[78:81], v[138:141], v[226:229], v[78:81]
	v_mfma_f32_16x16x32_bf16 v[126:129], v[134:137], v[200:203], v[126:129]
	v_mfma_f32_16x16x32_bf16 v[122:125], v[142:145], v[200:203], v[122:125]
	v_mfma_f32_16x16x32_bf16 v[118:121], v[134:137], v[214:217], v[118:121]
	v_mfma_f32_16x16x32_bf16 v[110:113], v[142:145], v[214:217], v[110:113]
	v_mfma_f32_16x16x32_bf16 v[102:105], v[134:137], v[222:225], v[102:105]
	v_mfma_f32_16x16x32_bf16 v[94:97], v[142:145], v[222:225], v[94:97]
	v_mfma_f32_16x16x32_bf16 v[86:89], v[134:137], v[230:233], v[86:89]
	v_mfma_f32_16x16x32_bf16 v[78:81], v[142:145], v[230:233], v[78:81]
	v_mfma_f32_16x16x32_bf16 v[114:117], v[170:173], v[196:199], v[114:117]
	v_mfma_f32_16x16x32_bf16 v[106:109], v[188:191], v[196:199], v[106:109]
	v_mfma_f32_16x16x32_bf16 v[98:101], v[170:173], v[210:213], v[98:101]
	v_mfma_f32_16x16x32_bf16 v[90:93], v[188:191], v[210:213], v[90:93]
	v_mfma_f32_16x16x32_bf16 v[82:85], v[170:173], v[218:221], v[82:85]
	v_mfma_f32_16x16x32_bf16 v[74:77], v[188:191], v[218:221], v[74:77]
	v_mfma_f32_16x16x32_bf16 v[70:73], v[170:173], v[226:229], v[70:73]
	v_mfma_f32_16x16x32_bf16 v[66:69], v[188:191], v[226:229], v[66:69]
	v_mfma_f32_16x16x32_bf16 v[114:117], v[184:187], v[200:203], v[114:117]
	v_mfma_f32_16x16x32_bf16 v[106:109], v[192:195], v[200:203], v[106:109]
	v_mfma_f32_16x16x32_bf16 v[98:101], v[184:187], v[214:217], v[98:101]
	v_mfma_f32_16x16x32_bf16 v[90:93], v[192:195], v[214:217], v[90:93]
	v_mfma_f32_16x16x32_bf16 v[82:85], v[184:187], v[222:225], v[82:85]
	v_mfma_f32_16x16x32_bf16 v[74:77], v[192:195], v[222:225], v[74:77]
	v_mfma_f32_16x16x32_bf16 v[70:73], v[184:187], v[230:233], v[70:73]
	v_mfma_f32_16x16x32_bf16 v[66:69], v[192:195], v[230:233], v[66:69]
	s_barrier
	s_setprio 2
	s_add_i32 s52, s52, s5
	s_mov_b32 m0, s52
	ds_read_b128 v[196:199], v183 offset:16384
	ds_read_b128 v[200:203], v183 offset:17408
	ds_read_b128 v[210:213], v183 offset:18432
	ds_read_b128 v[214:217], v183 offset:19456
	ds_read_b128 v[218:221], v183 offset:20480
	ds_read_b128 v[222:225], v183 offset:21504
	ds_read_b128 v[226:229], v183 offset:22528
	ds_read_b128 v[230:233], v183 offset:23552
	global_load_lds_dwordx4 v162, s[42:43]
	s_add_i32 m0, s52, 0x2000
	s_add_u32 s52, s42, 0x80000
	s_addc_u32 s53, s43, 0
	s_add_i32 s54, s54, s5
	global_load_lds_dwordx4 v158, s[42:43]
	s_mov_b32 m0, s54
	s_nop 0
	global_load_lds_dwordx4 v162, s[52:53]
	s_add_i32 m0, s54, 0x2000
	s_nop 0
	global_load_lds_dwordx4 v158, s[52:53]
	s_mov_b32 m0, s14
	s_nop 0
	global_load_lds_dwordx4 v164, s[44:45]
	s_mov_b32 m0, s15
	s_nop 0
	global_load_lds_dwordx4 v160, s[44:45]
	s_add_u32 s98, s42, 0x80
	s_addc_u32 s99, s43, 0
	s_add_u32 s100, s44, 0x80
	s_addc_u32 s101, s45, 0
	s_setprio 0
	s_waitcnt vmcnt(8) lgkmcnt(0)
	s_barrier
	v_mfma_f32_16x16x32_bf16 v[62:65], v[130:133], v[196:199], v[62:65]
	v_mfma_f32_16x16x32_bf16 v[58:61], v[138:141], v[196:199], v[58:61]
	v_mfma_f32_16x16x32_bf16 v[54:57], v[130:133], v[210:213], v[54:57]
	v_mfma_f32_16x16x32_bf16 v[46:49], v[138:141], v[210:213], v[46:49]
	v_mfma_f32_16x16x32_bf16 v[38:41], v[130:133], v[218:221], v[38:41]
	v_mfma_f32_16x16x32_bf16 v[30:33], v[138:141], v[218:221], v[30:33]
	v_mfma_f32_16x16x32_bf16 v[22:25], v[130:133], v[226:229], v[22:25]
	v_mfma_f32_16x16x32_bf16 v[14:17], v[138:141], v[226:229], v[14:17]
	v_mfma_f32_16x16x32_bf16 v[62:65], v[134:137], v[200:203], v[62:65]
	v_mfma_f32_16x16x32_bf16 v[58:61], v[142:145], v[200:203], v[58:61]
	v_mfma_f32_16x16x32_bf16 v[54:57], v[134:137], v[214:217], v[54:57]
	v_mfma_f32_16x16x32_bf16 v[46:49], v[142:145], v[214:217], v[46:49]
	v_mfma_f32_16x16x32_bf16 v[38:41], v[134:137], v[222:225], v[38:41]
	v_mfma_f32_16x16x32_bf16 v[30:33], v[142:145], v[222:225], v[30:33]
	v_mfma_f32_16x16x32_bf16 v[22:25], v[134:137], v[230:233], v[22:25]
	v_mfma_f32_16x16x32_bf16 v[14:17], v[142:145], v[230:233], v[14:17]
	v_mfma_f32_16x16x32_bf16 v[50:53], v[170:173], v[196:199], v[50:53]
	v_mfma_f32_16x16x32_bf16 v[42:45], v[188:191], v[196:199], v[42:45]
	v_mfma_f32_16x16x32_bf16 v[34:37], v[170:173], v[210:213], v[34:37]
	v_mfma_f32_16x16x32_bf16 v[26:29], v[188:191], v[210:213], v[26:29]
	v_mfma_f32_16x16x32_bf16 v[18:21], v[170:173], v[218:221], v[18:21]
	v_mfma_f32_16x16x32_bf16 v[10:13], v[188:191], v[218:221], v[10:13]
	v_mfma_f32_16x16x32_bf16 v[6:9], v[170:173], v[226:229], v[6:9]
	v_mfma_f32_16x16x32_bf16 v[2:5], v[188:191], v[226:229], v[2:5]
	v_mfma_f32_16x16x32_bf16 v[50:53], v[184:187], v[200:203], v[50:53]
	v_mfma_f32_16x16x32_bf16 v[42:45], v[192:195], v[200:203], v[42:45]
	v_mfma_f32_16x16x32_bf16 v[34:37], v[184:187], v[214:217], v[34:37]
	v_mfma_f32_16x16x32_bf16 v[26:29], v[192:195], v[214:217], v[26:29]
	v_mfma_f32_16x16x32_bf16 v[18:21], v[184:187], v[222:225], v[18:21]
	v_mfma_f32_16x16x32_bf16 v[10:13], v[192:195], v[222:225], v[10:13]
	v_mfma_f32_16x16x32_bf16 v[6:9], v[184:187], v[230:233], v[6:9]
	v_mfma_f32_16x16x32_bf16 v[2:5], v[192:195], v[230:233], v[2:5]
	s_barrier
	s_setprio 2
	s_add_i32 s52, 0, 0x18000
	s_add_i32 s53, 0, 0x1c000
	ds_read_b128 v[130:133], v238
	ds_read_b128 v[134:137], v238 offset:1024
	ds_read_b128 v[138:141], v238 offset:2048
	ds_read_b128 v[142:145], v238 offset:3072
	ds_read_b128 v[170:173], v239
	ds_read_b128 v[184:187], v239 offset:1024
	ds_read_b128 v[188:191], v239 offset:2048
	ds_read_b128 v[192:195], v239 offset:3072
	s_add_u32 s44, s44, 0x80000
	s_addc_u32 s45, s45, 0
	s_mov_b32 m0, s16
	ds_read_b128 v[196:199], v183 offset:32768
	ds_read_b128 v[200:203], v183 offset:33792
	ds_read_b128 v[210:213], v183 offset:34816
	ds_read_b128 v[214:217], v183 offset:35840
	ds_read_b128 v[218:221], v183 offset:36864
	ds_read_b128 v[222:225], v183 offset:37888
	ds_read_b128 v[226:229], v183 offset:38912
	ds_read_b128 v[230:233], v183 offset:39936
	global_load_lds_dwordx4 v164, s[44:45]
	s_mov_b32 m0, s18
	s_nop 0
	global_load_lds_dwordx4 v160, s[44:45]
	s_setprio 0
	s_waitcnt vmcnt(8) lgkmcnt(0)
	s_barrier
	v_mfma_f32_16x16x32_bf16 v[126:129], v[130:133], v[196:199], v[126:129]
	v_mfma_f32_16x16x32_bf16 v[122:125], v[138:141], v[196:199], v[122:125]
	v_mfma_f32_16x16x32_bf16 v[118:121], v[130:133], v[210:213], v[118:121]
	v_mfma_f32_16x16x32_bf16 v[110:113], v[138:141], v[210:213], v[110:113]
	v_mfma_f32_16x16x32_bf16 v[102:105], v[130:133], v[218:221], v[102:105]
	v_mfma_f32_16x16x32_bf16 v[94:97], v[138:141], v[218:221], v[94:97]
	v_mfma_f32_16x16x32_bf16 v[86:89], v[130:133], v[226:229], v[86:89]
	v_mfma_f32_16x16x32_bf16 v[78:81], v[138:141], v[226:229], v[78:81]
	v_mfma_f32_16x16x32_bf16 v[126:129], v[134:137], v[200:203], v[126:129]
	v_mfma_f32_16x16x32_bf16 v[122:125], v[142:145], v[200:203], v[122:125]
	v_mfma_f32_16x16x32_bf16 v[118:121], v[134:137], v[214:217], v[118:121]
	v_mfma_f32_16x16x32_bf16 v[110:113], v[142:145], v[214:217], v[110:113]
	v_mfma_f32_16x16x32_bf16 v[102:105], v[134:137], v[222:225], v[102:105]
	v_mfma_f32_16x16x32_bf16 v[94:97], v[142:145], v[222:225], v[94:97]
	v_mfma_f32_16x16x32_bf16 v[86:89], v[134:137], v[230:233], v[86:89]
	v_mfma_f32_16x16x32_bf16 v[78:81], v[142:145], v[230:233], v[78:81]
	v_mfma_f32_16x16x32_bf16 v[114:117], v[170:173], v[196:199], v[114:117]
	v_mfma_f32_16x16x32_bf16 v[106:109], v[188:191], v[196:199], v[106:109]
	v_mfma_f32_16x16x32_bf16 v[98:101], v[170:173], v[210:213], v[98:101]
	v_mfma_f32_16x16x32_bf16 v[90:93], v[188:191], v[210:213], v[90:93]
	v_mfma_f32_16x16x32_bf16 v[82:85], v[170:173], v[218:221], v[82:85]
	v_mfma_f32_16x16x32_bf16 v[74:77], v[188:191], v[218:221], v[74:77]
	v_mfma_f32_16x16x32_bf16 v[70:73], v[170:173], v[226:229], v[70:73]
	v_mfma_f32_16x16x32_bf16 v[66:69], v[188:191], v[226:229], v[66:69]
	v_mfma_f32_16x16x32_bf16 v[114:117], v[184:187], v[200:203], v[114:117]
	v_mfma_f32_16x16x32_bf16 v[106:109], v[192:195], v[200:203], v[106:109]
	v_mfma_f32_16x16x32_bf16 v[98:101], v[184:187], v[214:217], v[98:101]
	v_mfma_f32_16x16x32_bf16 v[90:93], v[192:195], v[214:217], v[90:93]
	v_mfma_f32_16x16x32_bf16 v[82:85], v[184:187], v[222:225], v[82:85]
	v_mfma_f32_16x16x32_bf16 v[74:77], v[192:195], v[222:225], v[74:77]
	v_mfma_f32_16x16x32_bf16 v[70:73], v[184:187], v[230:233], v[70:73]
	v_mfma_f32_16x16x32_bf16 v[66:69], v[192:195], v[230:233], v[66:69]
	s_barrier
	s_setprio 2
	s_add_i32 s44, s52, s5
	s_mov_b32 m0, s44
	ds_read_b128 v[196:199], v183 offset:49152
	ds_read_b128 v[200:203], v183 offset:50176
	ds_read_b128 v[210:213], v183 offset:51200
	ds_read_b128 v[214:217], v183 offset:52224
	ds_read_b128 v[218:221], v183 offset:53248
	ds_read_b128 v[222:225], v183 offset:54272
	ds_read_b128 v[226:229], v183 offset:55296
	ds_read_b128 v[230:233], v183 offset:56320
	global_load_lds_dwordx4 v162, s[98:99]
	s_add_i32 m0, s44, 0x2000
	s_add_u32 s42, s42, 0x80080
	s_addc_u32 s43, s43, 0
	s_add_i32 s44, s53, s5
	global_load_lds_dwordx4 v158, s[98:99]
	s_mov_b32 m0, s44
	s_nop 0
	global_load_lds_dwordx4 v162, s[42:43]
	s_add_i32 m0, s44, 0x2000
	s_nop 0
	global_load_lds_dwordx4 v158, s[42:43]
	s_mov_b32 m0, s19
	s_nop 0
	global_load_lds_dwordx4 v164, s[100:101]
	s_mov_b32 m0, s25
	s_nop 0
	global_load_lds_dwordx4 v160, s[100:101]
	s_setprio 0
	s_waitcnt vmcnt(8) lgkmcnt(0)
	s_barrier
	v_mfma_f32_16x16x32_bf16 v[62:65], v[130:133], v[196:199], v[62:65]
	v_mfma_f32_16x16x32_bf16 v[58:61], v[138:141], v[196:199], v[58:61]
	v_mfma_f32_16x16x32_bf16 v[54:57], v[130:133], v[210:213], v[54:57]
	v_mfma_f32_16x16x32_bf16 v[46:49], v[138:141], v[210:213], v[46:49]
	v_mfma_f32_16x16x32_bf16 v[38:41], v[130:133], v[218:221], v[38:41]
	v_mfma_f32_16x16x32_bf16 v[30:33], v[138:141], v[218:221], v[30:33]
	v_mfma_f32_16x16x32_bf16 v[22:25], v[130:133], v[226:229], v[22:25]
	v_mfma_f32_16x16x32_bf16 v[14:17], v[138:141], v[226:229], v[14:17]
	v_mfma_f32_16x16x32_bf16 v[62:65], v[134:137], v[200:203], v[62:65]
	v_mfma_f32_16x16x32_bf16 v[58:61], v[142:145], v[200:203], v[58:61]
	v_mfma_f32_16x16x32_bf16 v[54:57], v[134:137], v[214:217], v[54:57]
	v_mfma_f32_16x16x32_bf16 v[46:49], v[142:145], v[214:217], v[46:49]
	v_mfma_f32_16x16x32_bf16 v[38:41], v[134:137], v[222:225], v[38:41]
	v_mfma_f32_16x16x32_bf16 v[30:33], v[142:145], v[222:225], v[30:33]
	v_mfma_f32_16x16x32_bf16 v[22:25], v[134:137], v[230:233], v[22:25]
	v_mfma_f32_16x16x32_bf16 v[14:17], v[142:145], v[230:233], v[14:17]
	v_mfma_f32_16x16x32_bf16 v[50:53], v[170:173], v[196:199], v[50:53]
	v_mfma_f32_16x16x32_bf16 v[42:45], v[188:191], v[196:199], v[42:45]
	v_mfma_f32_16x16x32_bf16 v[34:37], v[170:173], v[210:213], v[34:37]
	v_mfma_f32_16x16x32_bf16 v[26:29], v[188:191], v[210:213], v[26:29]
	v_mfma_f32_16x16x32_bf16 v[18:21], v[170:173], v[218:221], v[18:21]
	v_mfma_f32_16x16x32_bf16 v[10:13], v[188:191], v[218:221], v[10:13]
	v_mfma_f32_16x16x32_bf16 v[6:9], v[170:173], v[226:229], v[6:9]
	v_mfma_f32_16x16x32_bf16 v[2:5], v[188:191], v[226:229], v[2:5]
	v_mfma_f32_16x16x32_bf16 v[50:53], v[184:187], v[200:203], v[50:53]
	v_mfma_f32_16x16x32_bf16 v[42:45], v[192:195], v[200:203], v[42:45]
	v_mfma_f32_16x16x32_bf16 v[34:37], v[184:187], v[214:217], v[34:37]
	v_mfma_f32_16x16x32_bf16 v[26:29], v[192:195], v[214:217], v[26:29]
	v_mfma_f32_16x16x32_bf16 v[18:21], v[184:187], v[222:225], v[18:21]
	v_mfma_f32_16x16x32_bf16 v[10:13], v[192:195], v[222:225], v[10:13]
	v_mfma_f32_16x16x32_bf16 v[6:9], v[184:187], v[230:233], v[6:9]
	v_mfma_f32_16x16x32_bf16 v[2:5], v[192:195], v[230:233], v[2:5]
	s_barrier
	s_add_i32 s51, s51, 2
	s_add_u32 s40, s40, 0x100
	s_addc_u32 s41, s41, 0
	s_add_u32 s49, s49, 0x100
	s_addc_u32 s50, s50, 0
	s_cmp_gt_u32 s51, 29
	s_cbranch_scc0 .LBB0_169
	s_setprio 0
	s_and_b64 vcc, exec, s[8:9]
	s_cbranch_vccz .LBB0_172
	s_barrier

.LBB0_516:
	s_setprio 2
	s_add_u32 s46, s44, 0xfff80080
	s_addc_u32 s47, s45, -1
	s_add_i32 s58, 0, 0x10000
	s_cmp_eq_u32 s57, 28
	s_cselect_b32 s49, s21, s47
	s_cselect_b32 s48, s50, s46
	s_cselect_b32 s47, s13, s56
	s_cselect_b32 s46, s51, s55
	s_add_i32 s60, 0, 0x14000
	ds_read_b128 v[82:85], v236
	ds_read_b128 v[86:89], v236 offset:1024
	ds_read_b128 v[98:101], v236 offset:2048
	ds_read_b128 v[102:105], v236 offset:3072
	ds_read_b128 v[154:157], v237
	ds_read_b128 v[168:171], v237 offset:1024
	ds_read_b128 v[176:179], v237 offset:2048
	ds_read_b128 v[180:183], v237 offset:3072
	s_add_i32 m0, s14, 0xc000
	ds_read_b128 v[184:187], v174
	ds_read_b128 v[188:191], v174 offset:1024
	ds_read_b128 v[192:195], v174 offset:2048
	ds_read_b128 v[196:199], v174 offset:3072
	ds_read_b128 v[200:203], v174 offset:4096
	ds_read_b128 v[210:213], v174 offset:5120
	ds_read_b128 v[214:217], v174 offset:6144
	ds_read_b128 v[218:221], v174 offset:7168
	global_load_lds_dwordx4 v164, s[44:45]
	s_add_i32 m0, s14, 0xe000
	s_nop 0
	global_load_lds_dwordx4 v166, s[44:45]
	s_setprio 0
	s_waitcnt vmcnt(8) lgkmcnt(0)
	s_barrier
	v_mfma_f32_16x16x32_bf16 v[142:145], v[82:85], v[184:187], v[142:145]
	v_mfma_f32_16x16x32_bf16 v[138:141], v[98:101], v[184:187], v[138:141]
	v_mfma_f32_16x16x32_bf16 v[126:129], v[82:85], v[192:195], v[126:129]
	v_mfma_f32_16x16x32_bf16 v[122:125], v[98:101], v[192:195], v[122:125]
	v_mfma_f32_16x16x32_bf16 v[110:113], v[82:85], v[200:203], v[110:113]
	v_mfma_f32_16x16x32_bf16 v[106:109], v[98:101], v[200:203], v[106:109]
	v_mfma_f32_16x16x32_bf16 v[78:81], v[82:85], v[214:217], v[78:81]
	v_mfma_f32_16x16x32_bf16 v[74:77], v[98:101], v[214:217], v[74:77]
	v_mfma_f32_16x16x32_bf16 v[142:145], v[86:89], v[188:191], v[142:145]
	v_mfma_f32_16x16x32_bf16 v[138:141], v[102:105], v[188:191], v[138:141]
	v_mfma_f32_16x16x32_bf16 v[126:129], v[86:89], v[196:199], v[126:129]
	v_mfma_f32_16x16x32_bf16 v[122:125], v[102:105], v[196:199], v[122:125]
	v_mfma_f32_16x16x32_bf16 v[110:113], v[86:89], v[210:213], v[110:113]
	v_mfma_f32_16x16x32_bf16 v[106:109], v[102:105], v[210:213], v[106:109]
	v_mfma_f32_16x16x32_bf16 v[78:81], v[86:89], v[218:221], v[78:81]
	v_mfma_f32_16x16x32_bf16 v[74:77], v[102:105], v[218:221], v[74:77]
	v_mfma_f32_16x16x32_bf16 v[134:137], v[154:157], v[184:187], v[134:137]
	v_mfma_f32_16x16x32_bf16 v[130:133], v[176:179], v[184:187], v[130:133]
	v_mfma_f32_16x16x32_bf16 v[118:121], v[154:157], v[192:195], v[118:121]
	v_mfma_f32_16x16x32_bf16 v[114:117], v[176:179], v[192:195], v[114:117]
	v_mfma_f32_16x16x32_bf16 v[94:97], v[154:157], v[200:203], v[94:97]
	v_mfma_f32_16x16x32_bf16 v[90:93], v[176:179], v[200:203], v[90:93]
	v_mfma_f32_16x16x32_bf16 v[70:73], v[154:157], v[214:217], v[70:73]
	v_mfma_f32_16x16x32_bf16 v[66:69], v[176:179], v[214:217], v[66:69]
	v_mfma_f32_16x16x32_bf16 v[134:137], v[168:171], v[188:191], v[134:137]
	v_mfma_f32_16x16x32_bf16 v[130:133], v[180:183], v[188:191], v[130:133]
	v_mfma_f32_16x16x32_bf16 v[118:121], v[168:171], v[196:199], v[118:121]
	v_mfma_f32_16x16x32_bf16 v[114:117], v[180:183], v[196:199], v[114:117]
	v_mfma_f32_16x16x32_bf16 v[94:97], v[168:171], v[210:213], v[94:97]
	v_mfma_f32_16x16x32_bf16 v[90:93], v[180:183], v[210:213], v[90:93]
	v_mfma_f32_16x16x32_bf16 v[70:73], v[168:171], v[218:221], v[70:73]
	v_mfma_f32_16x16x32_bf16 v[66:69], v[180:183], v[218:221], v[66:69]
	s_barrier
	s_setprio 2
	s_add_i32 s58, s58, s5
	s_mov_b32 m0, s58
	ds_read_b128 v[184:187], v174 offset:16384
	ds_read_b128 v[188:191], v174 offset:17408
	ds_read_b128 v[192:195], v174 offset:18432
	ds_read_b128 v[196:199], v174 offset:19456
	ds_read_b128 v[200:203], v174 offset:20480
	ds_read_b128 v[210:213], v174 offset:21504
	ds_read_b128 v[214:217], v174 offset:22528
	ds_read_b128 v[218:221], v174 offset:23552
	global_load_lds_dwordx4 v0, s[46:47]
	s_add_i32 m0, s58, 0x2000
	s_add_u32 s58, s46, 0x80000
	s_addc_u32 s59, s47, 0
	s_add_i32 s60, s60, s5
	global_load_lds_dwordx4 v158, s[46:47]
	s_mov_b32 m0, s60
	s_nop 0
	global_load_lds_dwordx4 v0, s[58:59]
	s_add_i32 m0, s60, 0x2000
	s_nop 0
	global_load_lds_dwordx4 v158, s[58:59]
	s_mov_b32 m0, s14
	s_nop 0
	global_load_lds_dwordx4 v162, s[48:49]
	s_mov_b32 m0, s15
	s_nop 0
	global_load_lds_dwordx4 v160, s[48:49]
	s_add_u32 s98, s46, 0x80
	s_addc_u32 s99, s47, 0
	s_add_u32 s100, s48, 0x80
	s_addc_u32 s101, s49, 0
	s_setprio 0
	s_waitcnt vmcnt(8) lgkmcnt(0)
	s_barrier
	v_mfma_f32_16x16x32_bf16 v[62:65], v[82:85], v[184:187], v[62:65]
	v_mfma_f32_16x16x32_bf16 v[58:61], v[98:101], v[184:187], v[58:61]
	v_mfma_f32_16x16x32_bf16 v[46:49], v[82:85], v[192:195], v[46:49]
	v_mfma_f32_16x16x32_bf16 v[42:45], v[98:101], v[192:195], v[42:45]
	v_mfma_f32_16x16x32_bf16 v[30:33], v[82:85], v[200:203], v[30:33]
	v_mfma_f32_16x16x32_bf16 v[26:29], v[98:101], v[200:203], v[26:29]
	v_mfma_f32_16x16x32_bf16 v[14:17], v[82:85], v[214:217], v[14:17]
	v_mfma_f32_16x16x32_bf16 v[10:13], v[98:101], v[214:217], v[10:13]
	v_mfma_f32_16x16x32_bf16 v[62:65], v[86:89], v[188:191], v[62:65]
	v_mfma_f32_16x16x32_bf16 v[58:61], v[102:105], v[188:191], v[58:61]
	v_mfma_f32_16x16x32_bf16 v[46:49], v[86:89], v[196:199], v[46:49]
	v_mfma_f32_16x16x32_bf16 v[42:45], v[102:105], v[196:199], v[42:45]
	v_mfma_f32_16x16x32_bf16 v[30:33], v[86:89], v[210:213], v[30:33]
	v_mfma_f32_16x16x32_bf16 v[26:29], v[102:105], v[210:213], v[26:29]
	v_mfma_f32_16x16x32_bf16 v[14:17], v[86:89], v[218:221], v[14:17]
	v_mfma_f32_16x16x32_bf16 v[10:13], v[102:105], v[218:221], v[10:13]
	v_mfma_f32_16x16x32_bf16 v[54:57], v[154:157], v[184:187], v[54:57]
	v_mfma_f32_16x16x32_bf16 v[50:53], v[176:179], v[184:187], v[50:53]
	v_mfma_f32_16x16x32_bf16 v[38:41], v[154:157], v[192:195], v[38:41]
	v_mfma_f32_16x16x32_bf16 v[34:37], v[176:179], v[192:195], v[34:37]
	v_mfma_f32_16x16x32_bf16 v[22:25], v[154:157], v[200:203], v[22:25]
	v_mfma_f32_16x16x32_bf16 v[18:21], v[176:179], v[200:203], v[18:21]
	v_mfma_f32_16x16x32_bf16 v[6:9], v[154:157], v[214:217], v[6:9]
	v_mfma_f32_16x16x32_bf16 v[2:5], v[176:179], v[214:217], v[2:5]
	v_mfma_f32_16x16x32_bf16 v[54:57], v[168:171], v[188:191], v[54:57]
	v_mfma_f32_16x16x32_bf16 v[50:53], v[180:183], v[188:191], v[50:53]
	v_mfma_f32_16x16x32_bf16 v[38:41], v[168:171], v[196:199], v[38:41]
	v_mfma_f32_16x16x32_bf16 v[34:37], v[180:183], v[196:199], v[34:37]
	v_mfma_f32_16x16x32_bf16 v[22:25], v[168:171], v[210:213], v[22:25]
	v_mfma_f32_16x16x32_bf16 v[18:21], v[180:183], v[210:213], v[18:21]
	v_mfma_f32_16x16x32_bf16 v[6:9], v[168:171], v[218:221], v[6:9]
	v_mfma_f32_16x16x32_bf16 v[2:5], v[180:183], v[218:221], v[2:5]
	s_barrier
	s_setprio 2
	s_add_i32 s58, 0, 0x18000
	s_add_i32 s59, 0, 0x1c000
	ds_read_b128 v[82:85], v238
	ds_read_b128 v[86:89], v238 offset:1024
	ds_read_b128 v[98:101], v238 offset:2048
	ds_read_b128 v[102:105], v238 offset:3072
	ds_read_b128 v[154:157], v239
	ds_read_b128 v[168:171], v239 offset:1024
	ds_read_b128 v[176:179], v239 offset:2048
	ds_read_b128 v[180:183], v239 offset:3072
	s_add_u32 s48, s48, 0x80000
	s_addc_u32 s49, s49, 0
	s_mov_b32 m0, s16
	ds_read_b128 v[184:187], v174 offset:32768
	ds_read_b128 v[188:191], v174 offset:33792
	ds_read_b128 v[192:195], v174 offset:34816
	ds_read_b128 v[196:199], v174 offset:35840
	ds_read_b128 v[200:203], v174 offset:36864
	ds_read_b128 v[210:213], v174 offset:37888
	ds_read_b128 v[214:217], v174 offset:38912
	ds_read_b128 v[218:221], v174 offset:39936
	global_load_lds_dwordx4 v162, s[48:49]
	s_mov_b32 m0, s18
	s_nop 0
	global_load_lds_dwordx4 v160, s[48:49]
	s_setprio 0
	s_waitcnt vmcnt(8) lgkmcnt(0)
	s_barrier
	v_mfma_f32_16x16x32_bf16 v[142:145], v[82:85], v[184:187], v[142:145]
	v_mfma_f32_16x16x32_bf16 v[138:141], v[98:101], v[184:187], v[138:141]
	v_mfma_f32_16x16x32_bf16 v[126:129], v[82:85], v[192:195], v[126:129]
	v_mfma_f32_16x16x32_bf16 v[122:125], v[98:101], v[192:195], v[122:125]
	v_mfma_f32_16x16x32_bf16 v[110:113], v[82:85], v[200:203], v[110:113]
	v_mfma_f32_16x16x32_bf16 v[106:109], v[98:101], v[200:203], v[106:109]
	v_mfma_f32_16x16x32_bf16 v[78:81], v[82:85], v[214:217], v[78:81]
	v_mfma_f32_16x16x32_bf16 v[74:77], v[98:101], v[214:217], v[74:77]
	v_mfma_f32_16x16x32_bf16 v[142:145], v[86:89], v[188:191], v[142:145]
	v_mfma_f32_16x16x32_bf16 v[138:141], v[102:105], v[188:191], v[138:141]
	v_mfma_f32_16x16x32_bf16 v[126:129], v[86:89], v[196:199], v[126:129]
	v_mfma_f32_16x16x32_bf16 v[122:125], v[102:105], v[196:199], v[122:125]
	v_mfma_f32_16x16x32_bf16 v[110:113], v[86:89], v[210:213], v[110:113]
	v_mfma_f32_16x16x32_bf16 v[106:109], v[102:105], v[210:213], v[106:109]
	v_mfma_f32_16x16x32_bf16 v[78:81], v[86:89], v[218:221], v[78:81]
	v_mfma_f32_16x16x32_bf16 v[74:77], v[102:105], v[218:221], v[74:77]
	v_mfma_f32_16x16x32_bf16 v[134:137], v[154:157], v[184:187], v[134:137]
	v_mfma_f32_16x16x32_bf16 v[130:133], v[176:179], v[184:187], v[130:133]
	v_mfma_f32_16x16x32_bf16 v[118:121], v[154:157], v[192:195], v[118:121]
	v_mfma_f32_16x16x32_bf16 v[114:117], v[176:179], v[192:195], v[114:117]
	v_mfma_f32_16x16x32_bf16 v[94:97], v[154:157], v[200:203], v[94:97]
	v_mfma_f32_16x16x32_bf16 v[90:93], v[176:179], v[200:203], v[90:93]
	v_mfma_f32_16x16x32_bf16 v[70:73], v[154:157], v[214:217], v[70:73]
	v_mfma_f32_16x16x32_bf16 v[66:69], v[176:179], v[214:217], v[66:69]
	v_mfma_f32_16x16x32_bf16 v[134:137], v[168:171], v[188:191], v[134:137]
	v_mfma_f32_16x16x32_bf16 v[130:133], v[180:183], v[188:191], v[130:133]
	v_mfma_f32_16x16x32_bf16 v[118:121], v[168:171], v[196:199], v[118:121]
	v_mfma_f32_16x16x32_bf16 v[114:117], v[180:183], v[196:199], v[114:117]
	v_mfma_f32_16x16x32_bf16 v[94:97], v[168:171], v[210:213], v[94:97]
	v_mfma_f32_16x16x32_bf16 v[90:93], v[180:183], v[210:213], v[90:93]
	v_mfma_f32_16x16x32_bf16 v[70:73], v[168:171], v[218:221], v[70:73]
	v_mfma_f32_16x16x32_bf16 v[66:69], v[180:183], v[218:221], v[66:69]
	s_barrier
	s_setprio 2
	s_add_i32 s48, s58, s5
	s_mov_b32 m0, s48
	ds_read_b128 v[184:187], v174 offset:49152
	ds_read_b128 v[188:191], v174 offset:50176
	ds_read_b128 v[192:195], v174 offset:51200
	ds_read_b128 v[196:199], v174 offset:52224
	ds_read_b128 v[200:203], v174 offset:53248
	ds_read_b128 v[210:213], v174 offset:54272
	ds_read_b128 v[214:217], v174 offset:55296
	ds_read_b128 v[218:221], v174 offset:56320
	global_load_lds_dwordx4 v0, s[98:99]
	s_add_i32 m0, s48, 0x2000
	s_add_u32 s46, s46, 0x80080
	s_addc_u32 s47, s47, 0
	s_add_i32 s48, s59, s5
	global_load_lds_dwordx4 v158, s[98:99]
	s_mov_b32 m0, s48
	s_nop 0
	global_load_lds_dwordx4 v0, s[46:47]
	s_add_i32 m0, s48, 0x2000
	s_nop 0
	global_load_lds_dwordx4 v158, s[46:47]
	s_mov_b32 m0, s25
	s_nop 0
	global_load_lds_dwordx4 v162, s[100:101]
	s_mov_b32 m0, s33
	s_nop 0
	global_load_lds_dwordx4 v160, s[100:101]
	s_setprio 0
	s_waitcnt vmcnt(8) lgkmcnt(0)
	s_barrier
	v_mfma_f32_16x16x32_bf16 v[62:65], v[82:85], v[184:187], v[62:65]
	v_mfma_f32_16x16x32_bf16 v[58:61], v[98:101], v[184:187], v[58:61]
	v_mfma_f32_16x16x32_bf16 v[46:49], v[82:85], v[192:195], v[46:49]
	v_mfma_f32_16x16x32_bf16 v[42:45], v[98:101], v[192:195], v[42:45]
	v_mfma_f32_16x16x32_bf16 v[30:33], v[82:85], v[200:203], v[30:33]
	v_mfma_f32_16x16x32_bf16 v[26:29], v[98:101], v[200:203], v[26:29]
	v_mfma_f32_16x16x32_bf16 v[14:17], v[82:85], v[214:217], v[14:17]
	v_mfma_f32_16x16x32_bf16 v[10:13], v[98:101], v[214:217], v[10:13]
	v_mfma_f32_16x16x32_bf16 v[62:65], v[86:89], v[188:191], v[62:65]
	v_mfma_f32_16x16x32_bf16 v[58:61], v[102:105], v[188:191], v[58:61]
	v_mfma_f32_16x16x32_bf16 v[46:49], v[86:89], v[196:199], v[46:49]
	v_mfma_f32_16x16x32_bf16 v[42:45], v[102:105], v[196:199], v[42:45]
	v_mfma_f32_16x16x32_bf16 v[30:33], v[86:89], v[210:213], v[30:33]
	v_mfma_f32_16x16x32_bf16 v[26:29], v[102:105], v[210:213], v[26:29]
	v_mfma_f32_16x16x32_bf16 v[14:17], v[86:89], v[218:221], v[14:17]
	v_mfma_f32_16x16x32_bf16 v[10:13], v[102:105], v[218:221], v[10:13]
	v_mfma_f32_16x16x32_bf16 v[54:57], v[154:157], v[184:187], v[54:57]
	v_mfma_f32_16x16x32_bf16 v[50:53], v[176:179], v[184:187], v[50:53]
	v_mfma_f32_16x16x32_bf16 v[38:41], v[154:157], v[192:195], v[38:41]
	v_mfma_f32_16x16x32_bf16 v[34:37], v[176:179], v[192:195], v[34:37]
	v_mfma_f32_16x16x32_bf16 v[22:25], v[154:157], v[200:203], v[22:25]
	v_mfma_f32_16x16x32_bf16 v[18:21], v[176:179], v[200:203], v[18:21]
	v_mfma_f32_16x16x32_bf16 v[6:9], v[154:157], v[214:217], v[6:9]
	v_mfma_f32_16x16x32_bf16 v[2:5], v[176:179], v[214:217], v[2:5]
	v_mfma_f32_16x16x32_bf16 v[54:57], v[168:171], v[188:191], v[54:57]
	v_mfma_f32_16x16x32_bf16 v[50:53], v[180:183], v[188:191], v[50:53]
	v_mfma_f32_16x16x32_bf16 v[38:41], v[168:171], v[196:199], v[38:41]
	v_mfma_f32_16x16x32_bf16 v[34:37], v[180:183], v[196:199], v[34:37]
	v_mfma_f32_16x16x32_bf16 v[22:25], v[168:171], v[210:213], v[22:25]
	v_mfma_f32_16x16x32_bf16 v[18:21], v[180:183], v[210:213], v[18:21]
	v_mfma_f32_16x16x32_bf16 v[6:9], v[168:171], v[218:221], v[6:9]
	v_mfma_f32_16x16x32_bf16 v[2:5], v[180:183], v[218:221], v[2:5]
	s_barrier
	s_add_i32 s57, s57, 2
	s_add_u32 s44, s44, 0x100
	s_addc_u32 s45, s45, 0
	s_add_u32 s55, s55, 0x100
	s_addc_u32 s56, s56, 0
	s_cmp_gt_u32 s57, 29
	s_cbranch_scc0 .LBB0_516
	s_setprio 0
	s_and_b64 vcc, exec, s[10:11]
	s_cbranch_vccz .LBB0_519
	s_barrier

.LBB0_604:
	s_setprio 2
	s_add_u32 s22, s6, 0xfff80080
	s_addc_u32 s23, s7, -1
	s_add_i32 s54, 0, 0x10000
	s_cmp_eq_u32 s53, 28
	s_cselect_b32 s47, s18, s23
	s_cselect_b32 s46, s19, s22
	s_cselect_b32 s23, s21, s52
	s_cselect_b32 s22, s25, s41
	s_add_i32 s56, 0, 0x14000
	ds_read_b128 v[130:133], v236
	ds_read_b128 v[134:137], v236 offset:1024
	ds_read_b128 v[154:157], v236 offset:2048
	ds_read_b128 v[162:165], v236 offset:3072
	ds_read_b128 v[166:169], v237
	ds_read_b128 v[170:173], v237 offset:1024
	ds_read_b128 v[180:183], v237 offset:2048
	ds_read_b128 v[184:187], v237 offset:3072
	s_add_i32 m0, s16, 0xc000
	ds_read_b128 v[188:191], v179
	ds_read_b128 v[192:195], v179 offset:1024
	ds_read_b128 v[196:199], v179 offset:2048
	ds_read_b128 v[200:203], v179 offset:3072
	ds_read_b128 v[210:213], v179 offset:4096
	ds_read_b128 v[214:217], v179 offset:5120
	ds_read_b128 v[218:221], v179 offset:6144
	ds_read_b128 v[222:225], v179 offset:7168
	global_load_lds_dwordx4 v158, s[6:7]
	s_add_i32 m0, s16, 0xe000
	s_nop 0
	global_load_lds_dwordx4 v160, s[6:7]
	s_setprio 0
	s_waitcnt vmcnt(8) lgkmcnt(0)
	s_barrier
	v_mfma_f32_16x16x32_bf16 v[126:129], v[130:133], v[188:191], v[126:129]
	v_mfma_f32_16x16x32_bf16 v[122:125], v[154:157], v[188:191], v[122:125]
	v_mfma_f32_16x16x32_bf16 v[110:113], v[130:133], v[196:199], v[110:113]
	v_mfma_f32_16x16x32_bf16 v[106:109], v[154:157], v[196:199], v[106:109]
	v_mfma_f32_16x16x32_bf16 v[94:97], v[130:133], v[210:213], v[94:97]
	v_mfma_f32_16x16x32_bf16 v[90:93], v[154:157], v[210:213], v[90:93]
	v_mfma_f32_16x16x32_bf16 v[78:81], v[130:133], v[218:221], v[78:81]
	v_mfma_f32_16x16x32_bf16 v[74:77], v[154:157], v[218:221], v[74:77]
	v_mfma_f32_16x16x32_bf16 v[126:129], v[134:137], v[192:195], v[126:129]
	v_mfma_f32_16x16x32_bf16 v[122:125], v[162:165], v[192:195], v[122:125]
	v_mfma_f32_16x16x32_bf16 v[110:113], v[134:137], v[200:203], v[110:113]
	v_mfma_f32_16x16x32_bf16 v[106:109], v[162:165], v[200:203], v[106:109]
	v_mfma_f32_16x16x32_bf16 v[94:97], v[134:137], v[214:217], v[94:97]
	v_mfma_f32_16x16x32_bf16 v[90:93], v[162:165], v[214:217], v[90:93]
	v_mfma_f32_16x16x32_bf16 v[78:81], v[134:137], v[222:225], v[78:81]
	v_mfma_f32_16x16x32_bf16 v[74:77], v[162:165], v[222:225], v[74:77]
	v_mfma_f32_16x16x32_bf16 v[118:121], v[166:169], v[188:191], v[118:121]
	v_mfma_f32_16x16x32_bf16 v[114:117], v[180:183], v[188:191], v[114:117]
	v_mfma_f32_16x16x32_bf16 v[102:105], v[166:169], v[196:199], v[102:105]
	v_mfma_f32_16x16x32_bf16 v[98:101], v[180:183], v[196:199], v[98:101]
	v_mfma_f32_16x16x32_bf16 v[86:89], v[166:169], v[210:213], v[86:89]
	v_mfma_f32_16x16x32_bf16 v[82:85], v[180:183], v[210:213], v[82:85]
	v_mfma_f32_16x16x32_bf16 v[70:73], v[166:169], v[218:221], v[70:73]
	v_mfma_f32_16x16x32_bf16 v[66:69], v[180:183], v[218:221], v[66:69]
	v_mfma_f32_16x16x32_bf16 v[118:121], v[170:173], v[192:195], v[118:121]
	v_mfma_f32_16x16x32_bf16 v[114:117], v[184:187], v[192:195], v[114:117]
	v_mfma_f32_16x16x32_bf16 v[102:105], v[170:173], v[200:203], v[102:105]
	v_mfma_f32_16x16x32_bf16 v[98:101], v[184:187], v[200:203], v[98:101]
	v_mfma_f32_16x16x32_bf16 v[86:89], v[170:173], v[214:217], v[86:89]
	v_mfma_f32_16x16x32_bf16 v[82:85], v[184:187], v[214:217], v[82:85]
	v_mfma_f32_16x16x32_bf16 v[70:73], v[170:173], v[222:225], v[70:73]
	v_mfma_f32_16x16x32_bf16 v[66:69], v[184:187], v[222:225], v[66:69]
	s_barrier
	s_setprio 2
	s_add_i32 s54, s54, s15
	s_mov_b32 m0, s54
	ds_read_b128 v[188:191], v179 offset:16384
	ds_read_b128 v[192:195], v179 offset:17408
	ds_read_b128 v[196:199], v179 offset:18432
	ds_read_b128 v[200:203], v179 offset:19456
	ds_read_b128 v[210:213], v179 offset:20480
	ds_read_b128 v[214:217], v179 offset:21504
	ds_read_b128 v[218:221], v179 offset:22528
	ds_read_b128 v[222:225], v179 offset:23552
	global_load_lds_dwordx4 v142, s[22:23]
	s_add_i32 m0, s54, 0x2000
	s_add_u32 s54, s22, 0x80000
	s_addc_u32 s55, s23, 0
	s_add_i32 s56, s56, s15
	global_load_lds_dwordx4 v138, s[22:23]
	s_mov_b32 m0, s56
	s_nop 0
	global_load_lds_dwordx4 v142, s[54:55]
	s_add_i32 m0, s56, 0x2000
	s_nop 0
	global_load_lds_dwordx4 v138, s[54:55]
	s_mov_b32 m0, s16
	s_nop 0
	global_load_lds_dwordx4 v144, s[46:47]
	s_mov_b32 m0, s33
	s_nop 0
	global_load_lds_dwordx4 v140, s[46:47]
	s_add_u32 s98, s22, 0x80
	s_addc_u32 s99, s23, 0
	s_add_u32 s100, s46, 0x80
	s_addc_u32 s101, s47, 0
	s_setprio 0
	s_waitcnt vmcnt(8) lgkmcnt(0)
	s_barrier
	v_mfma_f32_16x16x32_bf16 v[62:65], v[130:133], v[188:191], v[62:65]
	v_mfma_f32_16x16x32_bf16 v[58:61], v[154:157], v[188:191], v[58:61]
	v_mfma_f32_16x16x32_bf16 v[46:49], v[130:133], v[196:199], v[46:49]
	v_mfma_f32_16x16x32_bf16 v[42:45], v[154:157], v[196:199], v[42:45]
	v_mfma_f32_16x16x32_bf16 v[30:33], v[130:133], v[210:213], v[30:33]
	v_mfma_f32_16x16x32_bf16 v[26:29], v[154:157], v[210:213], v[26:29]
	v_mfma_f32_16x16x32_bf16 v[14:17], v[130:133], v[218:221], v[14:17]
	v_mfma_f32_16x16x32_bf16 v[10:13], v[154:157], v[218:221], v[10:13]
	v_mfma_f32_16x16x32_bf16 v[62:65], v[134:137], v[192:195], v[62:65]
	v_mfma_f32_16x16x32_bf16 v[58:61], v[162:165], v[192:195], v[58:61]
	v_mfma_f32_16x16x32_bf16 v[46:49], v[134:137], v[200:203], v[46:49]
	v_mfma_f32_16x16x32_bf16 v[42:45], v[162:165], v[200:203], v[42:45]
	v_mfma_f32_16x16x32_bf16 v[30:33], v[134:137], v[214:217], v[30:33]
	v_mfma_f32_16x16x32_bf16 v[26:29], v[162:165], v[214:217], v[26:29]
	v_mfma_f32_16x16x32_bf16 v[14:17], v[134:137], v[222:225], v[14:17]
	v_mfma_f32_16x16x32_bf16 v[10:13], v[162:165], v[222:225], v[10:13]
	v_mfma_f32_16x16x32_bf16 v[54:57], v[166:169], v[188:191], v[54:57]
	v_mfma_f32_16x16x32_bf16 v[50:53], v[180:183], v[188:191], v[50:53]
	v_mfma_f32_16x16x32_bf16 v[38:41], v[166:169], v[196:199], v[38:41]
	v_mfma_f32_16x16x32_bf16 v[34:37], v[180:183], v[196:199], v[34:37]
	v_mfma_f32_16x16x32_bf16 v[22:25], v[166:169], v[210:213], v[22:25]
	v_mfma_f32_16x16x32_bf16 v[18:21], v[180:183], v[210:213], v[18:21]
	v_mfma_f32_16x16x32_bf16 v[6:9], v[166:169], v[218:221], v[6:9]
	v_mfma_f32_16x16x32_bf16 v[2:5], v[180:183], v[218:221], v[2:5]
	v_mfma_f32_16x16x32_bf16 v[54:57], v[170:173], v[192:195], v[54:57]
	v_mfma_f32_16x16x32_bf16 v[50:53], v[184:187], v[192:195], v[50:53]
	v_mfma_f32_16x16x32_bf16 v[38:41], v[170:173], v[200:203], v[38:41]
	v_mfma_f32_16x16x32_bf16 v[34:37], v[184:187], v[200:203], v[34:37]
	v_mfma_f32_16x16x32_bf16 v[22:25], v[170:173], v[214:217], v[22:25]
	v_mfma_f32_16x16x32_bf16 v[18:21], v[184:187], v[214:217], v[18:21]
	v_mfma_f32_16x16x32_bf16 v[6:9], v[170:173], v[222:225], v[6:9]
	v_mfma_f32_16x16x32_bf16 v[2:5], v[184:187], v[222:225], v[2:5]
	s_barrier
	s_setprio 2
	s_add_i32 s54, 0, 0x18000
	s_add_i32 s55, 0, 0x1c000
	ds_read_b128 v[130:133], v238
	ds_read_b128 v[134:137], v238 offset:1024
	ds_read_b128 v[154:157], v238 offset:2048
	ds_read_b128 v[162:165], v238 offset:3072
	ds_read_b128 v[166:169], v239
	ds_read_b128 v[170:173], v239 offset:1024
	ds_read_b128 v[180:183], v239 offset:2048
	ds_read_b128 v[184:187], v239 offset:3072
	s_add_u32 s46, s46, 0x80000
	s_addc_u32 s47, s47, 0
	s_mov_b32 m0, s37
	ds_read_b128 v[188:191], v179 offset:32768
	ds_read_b128 v[192:195], v179 offset:33792
	ds_read_b128 v[196:199], v179 offset:34816
	ds_read_b128 v[200:203], v179 offset:35840
	ds_read_b128 v[210:213], v179 offset:36864
	ds_read_b128 v[214:217], v179 offset:37888
	ds_read_b128 v[218:221], v179 offset:38912
	ds_read_b128 v[222:225], v179 offset:39936
	global_load_lds_dwordx4 v144, s[46:47]
	s_mov_b32 m0, s48
	s_nop 0
	global_load_lds_dwordx4 v140, s[46:47]
	s_setprio 0
	s_waitcnt vmcnt(8) lgkmcnt(0)
	s_barrier
	v_mfma_f32_16x16x32_bf16 v[126:129], v[130:133], v[188:191], v[126:129]
	v_mfma_f32_16x16x32_bf16 v[122:125], v[154:157], v[188:191], v[122:125]
	v_mfma_f32_16x16x32_bf16 v[110:113], v[130:133], v[196:199], v[110:113]
	v_mfma_f32_16x16x32_bf16 v[106:109], v[154:157], v[196:199], v[106:109]
	v_mfma_f32_16x16x32_bf16 v[94:97], v[130:133], v[210:213], v[94:97]
	v_mfma_f32_16x16x32_bf16 v[90:93], v[154:157], v[210:213], v[90:93]
	v_mfma_f32_16x16x32_bf16 v[78:81], v[130:133], v[218:221], v[78:81]
	v_mfma_f32_16x16x32_bf16 v[74:77], v[154:157], v[218:221], v[74:77]
	v_mfma_f32_16x16x32_bf16 v[126:129], v[134:137], v[192:195], v[126:129]
	v_mfma_f32_16x16x32_bf16 v[122:125], v[162:165], v[192:195], v[122:125]
	v_mfma_f32_16x16x32_bf16 v[110:113], v[134:137], v[200:203], v[110:113]
	v_mfma_f32_16x16x32_bf16 v[106:109], v[162:165], v[200:203], v[106:109]
	v_mfma_f32_16x16x32_bf16 v[94:97], v[134:137], v[214:217], v[94:97]
	v_mfma_f32_16x16x32_bf16 v[90:93], v[162:165], v[214:217], v[90:93]
	v_mfma_f32_16x16x32_bf16 v[78:81], v[134:137], v[222:225], v[78:81]
	v_mfma_f32_16x16x32_bf16 v[74:77], v[162:165], v[222:225], v[74:77]
	v_mfma_f32_16x16x32_bf16 v[118:121], v[166:169], v[188:191], v[118:121]
	v_mfma_f32_16x16x32_bf16 v[114:117], v[180:183], v[188:191], v[114:117]
	v_mfma_f32_16x16x32_bf16 v[102:105], v[166:169], v[196:199], v[102:105]
	v_mfma_f32_16x16x32_bf16 v[98:101], v[180:183], v[196:199], v[98:101]
	v_mfma_f32_16x16x32_bf16 v[86:89], v[166:169], v[210:213], v[86:89]
	v_mfma_f32_16x16x32_bf16 v[82:85], v[180:183], v[210:213], v[82:85]
	v_mfma_f32_16x16x32_bf16 v[70:73], v[166:169], v[218:221], v[70:73]
	v_mfma_f32_16x16x32_bf16 v[66:69], v[180:183], v[218:221], v[66:69]
	v_mfma_f32_16x16x32_bf16 v[118:121], v[170:173], v[192:195], v[118:121]
	v_mfma_f32_16x16x32_bf16 v[114:117], v[184:187], v[192:195], v[114:117]
	v_mfma_f32_16x16x32_bf16 v[102:105], v[170:173], v[200:203], v[102:105]
	v_mfma_f32_16x16x32_bf16 v[98:101], v[184:187], v[200:203], v[98:101]
	v_mfma_f32_16x16x32_bf16 v[86:89], v[170:173], v[214:217], v[86:89]
	v_mfma_f32_16x16x32_bf16 v[82:85], v[184:187], v[214:217], v[82:85]
	v_mfma_f32_16x16x32_bf16 v[70:73], v[170:173], v[222:225], v[70:73]
	v_mfma_f32_16x16x32_bf16 v[66:69], v[184:187], v[222:225], v[66:69]
	s_barrier
	s_setprio 2
	s_add_i32 s46, s54, s15
	s_mov_b32 m0, s46
	ds_read_b128 v[188:191], v179 offset:49152
	ds_read_b128 v[192:195], v179 offset:50176
	ds_read_b128 v[196:199], v179 offset:51200
	ds_read_b128 v[200:203], v179 offset:52224
	ds_read_b128 v[210:213], v179 offset:53248
	ds_read_b128 v[214:217], v179 offset:54272
	ds_read_b128 v[218:221], v179 offset:55296
	ds_read_b128 v[222:225], v179 offset:56320
	global_load_lds_dwordx4 v142, s[98:99]
	s_add_i32 m0, s46, 0x2000
	s_add_u32 s22, s22, 0x80080
	s_addc_u32 s23, s23, 0
	s_add_i32 s46, s55, s15
	global_load_lds_dwordx4 v138, s[98:99]
	s_mov_b32 m0, s46
	s_nop 0
	global_load_lds_dwordx4 v142, s[22:23]
	s_add_i32 m0, s46, 0x2000
	s_nop 0
	global_load_lds_dwordx4 v138, s[22:23]
	s_mov_b32 m0, s49
	s_nop 0
	global_load_lds_dwordx4 v144, s[100:101]
	s_mov_b32 m0, s50
	s_nop 0
	global_load_lds_dwordx4 v140, s[100:101]
	s_setprio 0
	s_waitcnt vmcnt(8) lgkmcnt(0)
	s_barrier
	v_mfma_f32_16x16x32_bf16 v[62:65], v[130:133], v[188:191], v[62:65]
	v_mfma_f32_16x16x32_bf16 v[58:61], v[154:157], v[188:191], v[58:61]
	v_mfma_f32_16x16x32_bf16 v[46:49], v[130:133], v[196:199], v[46:49]
	v_mfma_f32_16x16x32_bf16 v[42:45], v[154:157], v[196:199], v[42:45]
	v_mfma_f32_16x16x32_bf16 v[30:33], v[130:133], v[210:213], v[30:33]
	v_mfma_f32_16x16x32_bf16 v[26:29], v[154:157], v[210:213], v[26:29]
	v_mfma_f32_16x16x32_bf16 v[14:17], v[130:133], v[218:221], v[14:17]
	v_mfma_f32_16x16x32_bf16 v[10:13], v[154:157], v[218:221], v[10:13]
	v_mfma_f32_16x16x32_bf16 v[62:65], v[134:137], v[192:195], v[62:65]
	v_mfma_f32_16x16x32_bf16 v[58:61], v[162:165], v[192:195], v[58:61]
	v_mfma_f32_16x16x32_bf16 v[46:49], v[134:137], v[200:203], v[46:49]
	v_mfma_f32_16x16x32_bf16 v[42:45], v[162:165], v[200:203], v[42:45]
	v_mfma_f32_16x16x32_bf16 v[30:33], v[134:137], v[214:217], v[30:33]
	v_mfma_f32_16x16x32_bf16 v[26:29], v[162:165], v[214:217], v[26:29]
	v_mfma_f32_16x16x32_bf16 v[14:17], v[134:137], v[222:225], v[14:17]
	v_mfma_f32_16x16x32_bf16 v[10:13], v[162:165], v[222:225], v[10:13]
	v_mfma_f32_16x16x32_bf16 v[54:57], v[166:169], v[188:191], v[54:57]
	v_mfma_f32_16x16x32_bf16 v[50:53], v[180:183], v[188:191], v[50:53]
	v_mfma_f32_16x16x32_bf16 v[38:41], v[166:169], v[196:199], v[38:41]
	v_mfma_f32_16x16x32_bf16 v[34:37], v[180:183], v[196:199], v[34:37]
	v_mfma_f32_16x16x32_bf16 v[22:25], v[166:169], v[210:213], v[22:25]
	v_mfma_f32_16x16x32_bf16 v[18:21], v[180:183], v[210:213], v[18:21]
	v_mfma_f32_16x16x32_bf16 v[6:9], v[166:169], v[218:221], v[6:9]
	v_mfma_f32_16x16x32_bf16 v[2:5], v[180:183], v[218:221], v[2:5]
	v_mfma_f32_16x16x32_bf16 v[54:57], v[170:173], v[192:195], v[54:57]
	v_mfma_f32_16x16x32_bf16 v[50:53], v[184:187], v[192:195], v[50:53]
	v_mfma_f32_16x16x32_bf16 v[38:41], v[170:173], v[200:203], v[38:41]
	v_mfma_f32_16x16x32_bf16 v[34:37], v[184:187], v[200:203], v[34:37]
	v_mfma_f32_16x16x32_bf16 v[22:25], v[170:173], v[214:217], v[22:25]
	v_mfma_f32_16x16x32_bf16 v[18:21], v[184:187], v[214:217], v[18:21]
	v_mfma_f32_16x16x32_bf16 v[6:9], v[170:173], v[222:225], v[6:9]
	v_mfma_f32_16x16x32_bf16 v[2:5], v[184:187], v[222:225], v[2:5]
	s_barrier
	s_add_i32 s53, s53, 2
	s_add_u32 s6, s6, 0x100
	s_addc_u32 s7, s7, 0
	s_add_u32 s41, s41, 0x100
	s_addc_u32 s52, s52, 0
	s_cmp_gt_u32 s53, 29
	s_cbranch_scc0 .LBB0_604
	s_setprio 0
	s_and_b64 vcc, exec, s[12:13]
	s_cbranch_vccz .LBB0_607
	s_barrier

.LBB0_728:
	s_setprio 2
	s_add_u32 s42, s22, 0x100
	s_addc_u32 s43, s23, 0
	s_add_i32 s50, 0, 0x10000
	s_cmpk_eq_i32 s25, 0x54
	s_cselect_b32 s49, s21, s43
	s_cselect_b32 s48, s20, s42
	s_cselect_b32 s47, s45, s19
	s_cselect_b32 s46, s44, s18
	s_add_i32 s51, 0, 0x14000
	ds_read_b128 v[42:45], v236
	ds_read_b128 v[46:49], v236 offset:1024
	ds_read_b128 v[50:53], v236 offset:2048
	ds_read_b128 v[54:57], v236 offset:3072
	ds_read_b128 v[154:157], v237
	ds_read_b128 v[168:171], v237 offset:1024
	ds_read_b128 v[172:175], v237 offset:2048
	ds_read_b128 v[180:183], v237 offset:3072
	s_add_i32 m0, s33, 0xc000
	ds_read_b128 v[184:187], v178
	ds_read_b128 v[188:191], v178 offset:1024
	ds_read_b128 v[192:195], v178 offset:2048
	ds_read_b128 v[196:199], v178 offset:3072
	ds_read_b128 v[200:203], v178 offset:4096
	ds_read_b128 v[210:213], v178 offset:5120
	ds_read_b128 v[214:217], v178 offset:6144
	ds_read_b128 v[218:221], v178 offset:7168
	global_load_lds_dwordx4 v164, s[22:23]
	s_add_i32 m0, s33, 0xe000
	s_nop 0
	global_load_lds_dwordx4 v166, s[22:23]
	s_setprio 0
	s_waitcnt vmcnt(8) lgkmcnt(0)
	s_barrier
	v_mfma_f32_16x16x32_bf16 v[142:145], v[42:45], v[184:187], v[142:145]
	v_mfma_f32_16x16x32_bf16 v[138:141], v[50:53], v[184:187], v[138:141]
	v_mfma_f32_16x16x32_bf16 v[126:129], v[42:45], v[192:195], v[126:129]
	v_mfma_f32_16x16x32_bf16 v[122:125], v[50:53], v[192:195], v[122:125]
	v_mfma_f32_16x16x32_bf16 v[110:113], v[42:45], v[200:203], v[110:113]
	v_mfma_f32_16x16x32_bf16 v[106:109], v[50:53], v[200:203], v[106:109]
	v_mfma_f32_16x16x32_bf16 v[94:97], v[42:45], v[214:217], v[94:97]
	v_mfma_f32_16x16x32_bf16 v[90:93], v[50:53], v[214:217], v[90:93]
	v_mfma_f32_16x16x32_bf16 v[142:145], v[46:49], v[188:191], v[142:145]
	v_mfma_f32_16x16x32_bf16 v[138:141], v[54:57], v[188:191], v[138:141]
	v_mfma_f32_16x16x32_bf16 v[126:129], v[46:49], v[196:199], v[126:129]
	v_mfma_f32_16x16x32_bf16 v[122:125], v[54:57], v[196:199], v[122:125]
	v_mfma_f32_16x16x32_bf16 v[110:113], v[46:49], v[210:213], v[110:113]
	v_mfma_f32_16x16x32_bf16 v[106:109], v[54:57], v[210:213], v[106:109]
	v_mfma_f32_16x16x32_bf16 v[94:97], v[46:49], v[218:221], v[94:97]
	v_mfma_f32_16x16x32_bf16 v[90:93], v[54:57], v[218:221], v[90:93]
	v_mfma_f32_16x16x32_bf16 v[134:137], v[154:157], v[184:187], v[134:137]
	v_mfma_f32_16x16x32_bf16 v[130:133], v[172:175], v[184:187], v[130:133]
	v_mfma_f32_16x16x32_bf16 v[118:121], v[154:157], v[192:195], v[118:121]
	v_mfma_f32_16x16x32_bf16 v[114:117], v[172:175], v[192:195], v[114:117]
	v_mfma_f32_16x16x32_bf16 v[102:105], v[154:157], v[200:203], v[102:105]
	v_mfma_f32_16x16x32_bf16 v[98:101], v[172:175], v[200:203], v[98:101]
	v_mfma_f32_16x16x32_bf16 v[86:89], v[154:157], v[214:217], v[86:89]
	v_mfma_f32_16x16x32_bf16 v[82:85], v[172:175], v[214:217], v[82:85]
	v_mfma_f32_16x16x32_bf16 v[134:137], v[168:171], v[188:191], v[134:137]
	v_mfma_f32_16x16x32_bf16 v[130:133], v[180:183], v[188:191], v[130:133]
	v_mfma_f32_16x16x32_bf16 v[118:121], v[168:171], v[196:199], v[118:121]
	v_mfma_f32_16x16x32_bf16 v[114:117], v[180:183], v[196:199], v[114:117]
	v_mfma_f32_16x16x32_bf16 v[102:105], v[168:171], v[210:213], v[102:105]
	v_mfma_f32_16x16x32_bf16 v[98:101], v[180:183], v[210:213], v[98:101]
	v_mfma_f32_16x16x32_bf16 v[86:89], v[168:171], v[218:221], v[86:89]
	v_mfma_f32_16x16x32_bf16 v[82:85], v[180:183], v[218:221], v[82:85]
	s_barrier
	s_setprio 2
	s_add_i32 s22, s50, s16
	s_mov_b32 m0, s22
	ds_read_b128 v[184:187], v178 offset:16384
	ds_read_b128 v[188:191], v178 offset:17408
	ds_read_b128 v[192:195], v178 offset:18432
	ds_read_b128 v[196:199], v178 offset:19456
	ds_read_b128 v[200:203], v178 offset:20480
	ds_read_b128 v[210:213], v178 offset:21504
	ds_read_b128 v[214:217], v178 offset:22528
	ds_read_b128 v[218:221], v178 offset:23552
	global_load_lds_dwordx4 v0, s[46:47]
	s_add_i32 m0, s22, 0x2000
	s_add_u32 s22, s46, 0x160000
	s_addc_u32 s23, s47, 0
	s_add_i32 s50, s51, s16
	global_load_lds_dwordx4 v158, s[46:47]
	s_mov_b32 m0, s50
	s_nop 0
	global_load_lds_dwordx4 v0, s[22:23]
	s_add_i32 m0, s50, 0x2000
	s_nop 0
	global_load_lds_dwordx4 v158, s[22:23]
	s_mov_b32 m0, s33
	s_nop 0
	global_load_lds_dwordx4 v162, s[48:49]
	s_mov_b32 m0, s37
	s_nop 0
	global_load_lds_dwordx4 v160, s[48:49]
	s_add_u32 s98, s46, 0x80
	s_addc_u32 s99, s47, 0
	s_add_u32 s100, s48, 0x80
	s_addc_u32 s101, s49, 0
	s_setprio 0
	s_waitcnt vmcnt(8) lgkmcnt(0)
	s_barrier
	v_mfma_f32_16x16x32_bf16 v[78:81], v[42:45], v[184:187], v[78:81]
	v_mfma_f32_16x16x32_bf16 v[74:77], v[50:53], v[184:187], v[74:77]
	v_mfma_f32_16x16x32_bf16 v[62:65], v[42:45], v[192:195], v[62:65]
	v_mfma_f32_16x16x32_bf16 v[58:61], v[50:53], v[192:195], v[58:61]
	v_mfma_f32_16x16x32_bf16 v[30:33], v[42:45], v[200:203], v[30:33]
	v_mfma_f32_16x16x32_bf16 v[26:29], v[50:53], v[200:203], v[26:29]
	v_mfma_f32_16x16x32_bf16 v[14:17], v[42:45], v[214:217], v[14:17]
	v_mfma_f32_16x16x32_bf16 v[10:13], v[50:53], v[214:217], v[10:13]
	v_mfma_f32_16x16x32_bf16 v[78:81], v[46:49], v[188:191], v[78:81]
	v_mfma_f32_16x16x32_bf16 v[74:77], v[54:57], v[188:191], v[74:77]
	v_mfma_f32_16x16x32_bf16 v[62:65], v[46:49], v[196:199], v[62:65]
	v_mfma_f32_16x16x32_bf16 v[58:61], v[54:57], v[196:199], v[58:61]
	v_mfma_f32_16x16x32_bf16 v[30:33], v[46:49], v[210:213], v[30:33]
	v_mfma_f32_16x16x32_bf16 v[26:29], v[54:57], v[210:213], v[26:29]
	v_mfma_f32_16x16x32_bf16 v[14:17], v[46:49], v[218:221], v[14:17]
	v_mfma_f32_16x16x32_bf16 v[10:13], v[54:57], v[218:221], v[10:13]
	v_mfma_f32_16x16x32_bf16 v[38:41], v[154:157], v[192:195], v[38:41]
	v_mfma_f32_16x16x32_bf16 v[34:37], v[172:175], v[192:195], v[34:37]
	v_mfma_f32_16x16x32_bf16 v[22:25], v[154:157], v[200:203], v[22:25]
	v_mfma_f32_16x16x32_bf16 v[18:21], v[172:175], v[200:203], v[18:21]
	v_mfma_f32_16x16x32_bf16 v[6:9], v[154:157], v[214:217], v[6:9]
	v_mfma_f32_16x16x32_bf16 v[2:5], v[172:175], v[214:217], v[2:5]
	v_mfma_f32_16x16x32_bf16 v[42:45], v[154:157], v[184:187], v[70:73]
	v_mfma_f32_16x16x32_bf16 v[46:49], v[172:175], v[184:187], v[66:69]
	v_mfma_f32_16x16x32_bf16 v[38:41], v[168:171], v[196:199], v[38:41]
	v_mfma_f32_16x16x32_bf16 v[34:37], v[180:183], v[196:199], v[34:37]
	v_mfma_f32_16x16x32_bf16 v[22:25], v[168:171], v[210:213], v[22:25]
	v_mfma_f32_16x16x32_bf16 v[18:21], v[180:183], v[210:213], v[18:21]
	v_mfma_f32_16x16x32_bf16 v[6:9], v[168:171], v[218:221], v[6:9]
	v_mfma_f32_16x16x32_bf16 v[2:5], v[180:183], v[218:221], v[2:5]
	v_mfma_f32_16x16x32_bf16 v[42:45], v[168:171], v[188:191], v[42:45]
	v_mfma_f32_16x16x32_bf16 v[46:49], v[180:183], v[188:191], v[46:49]
	s_barrier
	s_setprio 2
	s_add_i32 s50, 0, 0x18000
	s_add_i32 s51, 0, 0x1c000
	ds_read_b128 v[50:53], v238
	ds_read_b128 v[54:57], v238 offset:1024
	ds_read_b128 v[66:69], v238 offset:2048
	ds_read_b128 v[70:73], v238 offset:3072
	ds_read_b128 v[154:157], v239
	ds_read_b128 v[168:171], v239 offset:1024
	ds_read_b128 v[172:175], v239 offset:2048
	ds_read_b128 v[180:183], v239 offset:3072
	s_add_u32 s22, s48, 0x160000
	s_addc_u32 s23, s49, 0
	s_mov_b32 m0, s52
	ds_read_b128 v[184:187], v178 offset:32768
	ds_read_b128 v[188:191], v178 offset:33792
	ds_read_b128 v[192:195], v178 offset:34816
	ds_read_b128 v[196:199], v178 offset:35840
	ds_read_b128 v[200:203], v178 offset:36864
	ds_read_b128 v[210:213], v178 offset:37888
	ds_read_b128 v[214:217], v178 offset:38912
	ds_read_b128 v[218:221], v178 offset:39936
	global_load_lds_dwordx4 v162, s[22:23]
	s_mov_b32 m0, s53
	s_nop 0
	global_load_lds_dwordx4 v160, s[22:23]
	s_setprio 0
	s_waitcnt vmcnt(8) lgkmcnt(0)
	s_barrier
	v_mfma_f32_16x16x32_bf16 v[142:145], v[50:53], v[184:187], v[142:145]
	v_mfma_f32_16x16x32_bf16 v[138:141], v[66:69], v[184:187], v[138:141]
	v_mfma_f32_16x16x32_bf16 v[126:129], v[50:53], v[192:195], v[126:129]
	v_mfma_f32_16x16x32_bf16 v[122:125], v[66:69], v[192:195], v[122:125]
	v_mfma_f32_16x16x32_bf16 v[110:113], v[50:53], v[200:203], v[110:113]
	v_mfma_f32_16x16x32_bf16 v[106:109], v[66:69], v[200:203], v[106:109]
	v_mfma_f32_16x16x32_bf16 v[94:97], v[50:53], v[214:217], v[94:97]
	v_mfma_f32_16x16x32_bf16 v[90:93], v[66:69], v[214:217], v[90:93]
	v_mfma_f32_16x16x32_bf16 v[142:145], v[54:57], v[188:191], v[142:145]
	v_mfma_f32_16x16x32_bf16 v[138:141], v[70:73], v[188:191], v[138:141]
	v_mfma_f32_16x16x32_bf16 v[126:129], v[54:57], v[196:199], v[126:129]
	v_mfma_f32_16x16x32_bf16 v[122:125], v[70:73], v[196:199], v[122:125]
	v_mfma_f32_16x16x32_bf16 v[110:113], v[54:57], v[210:213], v[110:113]
	v_mfma_f32_16x16x32_bf16 v[106:109], v[70:73], v[210:213], v[106:109]
	v_mfma_f32_16x16x32_bf16 v[94:97], v[54:57], v[218:221], v[94:97]
	v_mfma_f32_16x16x32_bf16 v[90:93], v[70:73], v[218:221], v[90:93]
	v_mfma_f32_16x16x32_bf16 v[134:137], v[154:157], v[184:187], v[134:137]
	v_mfma_f32_16x16x32_bf16 v[130:133], v[172:175], v[184:187], v[130:133]
	v_mfma_f32_16x16x32_bf16 v[118:121], v[154:157], v[192:195], v[118:121]
	v_mfma_f32_16x16x32_bf16 v[114:117], v[172:175], v[192:195], v[114:117]
	v_mfma_f32_16x16x32_bf16 v[102:105], v[154:157], v[200:203], v[102:105]
	v_mfma_f32_16x16x32_bf16 v[98:101], v[172:175], v[200:203], v[98:101]
	v_mfma_f32_16x16x32_bf16 v[86:89], v[154:157], v[214:217], v[86:89]
	v_mfma_f32_16x16x32_bf16 v[82:85], v[172:175], v[214:217], v[82:85]
	v_mfma_f32_16x16x32_bf16 v[134:137], v[168:171], v[188:191], v[134:137]
	v_mfma_f32_16x16x32_bf16 v[130:133], v[180:183], v[188:191], v[130:133]
	v_mfma_f32_16x16x32_bf16 v[118:121], v[168:171], v[196:199], v[118:121]
	v_mfma_f32_16x16x32_bf16 v[114:117], v[180:183], v[196:199], v[114:117]
	v_mfma_f32_16x16x32_bf16 v[102:105], v[168:171], v[210:213], v[102:105]
	v_mfma_f32_16x16x32_bf16 v[98:101], v[180:183], v[210:213], v[98:101]
	v_mfma_f32_16x16x32_bf16 v[86:89], v[168:171], v[218:221], v[86:89]
	v_mfma_f32_16x16x32_bf16 v[82:85], v[180:183], v[218:221], v[82:85]
	s_barrier
	s_setprio 2
	s_add_i32 s22, s50, s16
	s_mov_b32 m0, s22
	ds_read_b128 v[184:187], v178 offset:49152
	ds_read_b128 v[188:191], v178 offset:50176
	ds_read_b128 v[192:195], v178 offset:51200
	ds_read_b128 v[196:199], v178 offset:52224
	ds_read_b128 v[200:203], v178 offset:53248
	ds_read_b128 v[210:213], v178 offset:54272
	ds_read_b128 v[214:217], v178 offset:55296
	ds_read_b128 v[218:221], v178 offset:56320
	global_load_lds_dwordx4 v0, s[98:99]
	s_add_i32 m0, s22, 0x2000
	s_add_u32 s22, s46, 0x160080
	s_addc_u32 s23, s47, 0
	s_add_i32 s46, s51, s16
	global_load_lds_dwordx4 v158, s[98:99]
	s_mov_b32 m0, s46
	s_nop 0
	global_load_lds_dwordx4 v0, s[22:23]
	s_add_i32 m0, s46, 0x2000
	s_nop 0
	global_load_lds_dwordx4 v158, s[22:23]
	s_mov_b32 m0, s55
	s_nop 0
	global_load_lds_dwordx4 v162, s[100:101]
	s_mov_b32 m0, s56
	s_nop 0
	global_load_lds_dwordx4 v160, s[100:101]
	s_setprio 0
	s_waitcnt vmcnt(8) lgkmcnt(0)
	s_barrier
	v_mfma_f32_16x16x32_bf16 v[78:81], v[50:53], v[184:187], v[78:81]
	v_mfma_f32_16x16x32_bf16 v[74:77], v[66:69], v[184:187], v[74:77]
	v_mfma_f32_16x16x32_bf16 v[62:65], v[50:53], v[192:195], v[62:65]
	v_mfma_f32_16x16x32_bf16 v[58:61], v[66:69], v[192:195], v[58:61]
	v_mfma_f32_16x16x32_bf16 v[30:33], v[50:53], v[200:203], v[30:33]
	v_mfma_f32_16x16x32_bf16 v[26:29], v[66:69], v[200:203], v[26:29]
	v_mfma_f32_16x16x32_bf16 v[14:17], v[50:53], v[214:217], v[14:17]
	v_mfma_f32_16x16x32_bf16 v[10:13], v[66:69], v[214:217], v[10:13]
	v_mfma_f32_16x16x32_bf16 v[78:81], v[54:57], v[188:191], v[78:81]
	v_mfma_f32_16x16x32_bf16 v[74:77], v[70:73], v[188:191], v[74:77]
	v_mfma_f32_16x16x32_bf16 v[62:65], v[54:57], v[196:199], v[62:65]
	v_mfma_f32_16x16x32_bf16 v[58:61], v[70:73], v[196:199], v[58:61]
	v_mfma_f32_16x16x32_bf16 v[30:33], v[54:57], v[210:213], v[30:33]
	v_mfma_f32_16x16x32_bf16 v[26:29], v[70:73], v[210:213], v[26:29]
	v_mfma_f32_16x16x32_bf16 v[14:17], v[54:57], v[218:221], v[14:17]
	v_mfma_f32_16x16x32_bf16 v[10:13], v[70:73], v[218:221], v[10:13]
	v_mfma_f32_16x16x32_bf16 v[42:45], v[154:157], v[184:187], v[42:45]
	v_mfma_f32_16x16x32_bf16 v[70:73], v[168:171], v[188:191], v[42:45]
	v_mfma_f32_16x16x32_bf16 v[42:45], v[172:175], v[184:187], v[46:49]
	v_mfma_f32_16x16x32_bf16 v[38:41], v[154:157], v[192:195], v[38:41]
	v_mfma_f32_16x16x32_bf16 v[34:37], v[172:175], v[192:195], v[34:37]
	v_mfma_f32_16x16x32_bf16 v[22:25], v[154:157], v[200:203], v[22:25]
	v_mfma_f32_16x16x32_bf16 v[18:21], v[172:175], v[200:203], v[18:21]
	v_mfma_f32_16x16x32_bf16 v[6:9], v[154:157], v[214:217], v[6:9]
	v_mfma_f32_16x16x32_bf16 v[2:5], v[172:175], v[214:217], v[2:5]
	v_mfma_f32_16x16x32_bf16 v[66:69], v[180:183], v[188:191], v[42:45]
	v_mfma_f32_16x16x32_bf16 v[38:41], v[168:171], v[196:199], v[38:41]
	v_mfma_f32_16x16x32_bf16 v[34:37], v[180:183], v[196:199], v[34:37]
	v_mfma_f32_16x16x32_bf16 v[22:25], v[168:171], v[210:213], v[22:25]
	v_mfma_f32_16x16x32_bf16 v[18:21], v[180:183], v[210:213], v[18:21]
	v_mfma_f32_16x16x32_bf16 v[6:9], v[168:171], v[218:221], v[6:9]
	v_mfma_f32_16x16x32_bf16 v[2:5], v[180:183], v[218:221], v[2:5]
	s_barrier
	s_add_i32 s25, s25, 2
	s_add_u32 s18, s18, 0x100
	s_addc_u32 s19, s19, 0
	s_cmpk_gt_u32 s25, 0x55
	s_mov_b64 s[22:23], s[42:43]
	s_cbranch_scc0 .LBB0_728
	s_setprio 0
	s_and_b64 vcc, exec, s[12:13]
	s_cbranch_vccz .LBB0_731
	s_barrier
